# v18 + p128 operand loads batched 4-deep with scalar trip count (no shape assumptions)
# speedup vs baseline: 1.0009x; 1.0009x over previous
; __device__ __forceinline__ int obid() { extern __shared__ __attribute__((aligned(16))) unsigned char shm_vb[]; return __builtin_amdgcn_readfirstlane(*(volatile LAS int*)((LAS unsigned char*)shm_vb + VB_OFF)); }
; __device__ __forceinline__ void phase_p128(const bf16_t* __restrict__ dc, const bf16_t* __restrict__ zf, float* __restrict__ p128, LAS float* red, const int nseq, const int S) {
;     ...
;   for (int task = obid(); task < nrb * 2 * nseq; task += gridDim.x) {
;     const int seq = task / (2 * nrb), odd = (task / nrb) & 1, rb = task % nrb;
;     const int kap = rb * 16 + (lane & 15);
;     const bf16_t* ap = dc + (size_t)(2 * kap + odd) * rmul * DLD + 8 * (lane >> 4);
;     const bf16_t* bp = zf + (size_t)(2048 + (lane & 15)) * ZFLD + (size_t)seq * 2 * K2 + (size_t)odd * K2 + 8 * (lane >> 4);
;     f32x4 acc = {0.f, 0.f, 0.f, 0.f};
;     for (int ch = wid; ch < nchunk; ch += 8) {
;       const bf16x8 av = *(const bf16x8*)(ap + ch * 32), bv = *(const bf16x8*)(bp + ch * 32);
;       acc = __builtin_amdgcn_mfma_f32_16x16x32_bf16(av, bv, acc, 0, 0, 0);
;     }
.LBB0_416:
	s_abs_i32 s5, s18
	s_mul_hi_u32 s6, s5, s34
	s_mul_i32 s7, s6, s31
	s_sub_i32 s7, s5, s7
	s_ashr_i32 s4, s18, 31
	s_add_i32 s8, s6, 1
	s_sub_i32 s9, s7, s31
	s_cmp_ge_u32 s7, s31
	s_cselect_b32 s6, s8, s6
	s_cselect_b32 s7, s9, s7
	s_add_i32 s8, s6, 1
	s_cmp_ge_u32 s7, s31
	s_mul_hi_u32 s7, s5, s35
	s_cselect_b32 s6, s8, s6
	s_mul_i32 s8, s7, s29
	s_xor_b32 s6, s6, s4
	s_sub_i32 s5, s5, s8
	s_sub_i32 s6, s6, s4
	s_add_i32 s8, s7, 1
	s_sub_i32 s9, s5, s29
	s_cmp_ge_u32 s5, s29
	s_cselect_b32 s7, s8, s7
	s_cselect_b32 s5, s9, s5
	s_add_i32 s8, s7, 1
	s_cmp_ge_u32 s5, s29
	s_cselect_b32 s5, s8, s7
	s_xor_b32 s5, s5, s4
	s_sub_i32 s4, s5, s4
	s_and_b32 s39, s4, 1
	s_mul_i32 s4, s4, s29
	s_sub_i32 s4, s18, s4
	v_mov_b32_e32 v3, 0
	s_lshl_b32 s41, s4, 4
	s_ashr_i32 s7, s6, 31
	v_mov_b32_e32 v2, v3
	v_mov_b32_e32 v1, v3
	v_mov_b32_e32 v0, v3
	s_and_saveexec_b64 s[8:9], vcc
	s_cbranch_execz .LBB0_420
	v_or_b32_e32 v0, s41, v4
	s_mul_i32 s22, s13, s39
	v_lshl_or_b32 v0, v0, 1, s39
	s_mul_i32 s4, s38, s6
	s_lshl_b32 s22, s22, 1
	v_ashrrev_i32_e32 v1, 31, v0
	s_mul_hi_i32 s5, s38, s6
	s_add_u32 s4, s4, s22
	v_lshlrev_b64 v[0:1], s1, v[0:1]
	s_addc_u32 s5, s5, 0
	s_movk_i32 s22, 0x2200
	v_lshl_add_u64 v[10:11], v[6:7], 0, s[4:5]
	v_mad_u64_u32 v[12:13], s[4:5], v0, s22, v[8:9]
	v_mov_b32_e32 v0, v13
	v_mad_u64_u32 v[0:1], s[4:5], v1, s22, v[0:1]
	v_mov_b32_e32 v13, v0
	v_mov_b32_e32 v0, 0
	s_mov_b64 s[36:37], 0
	v_mov_b32_e32 v17, v5
	v_mov_b32_e32 v1, v0
	v_mov_b32_e32 v2, v0
	v_mov_b32_e32 v3, v0
	v_readfirstlane_b32 s100, v5
	s_nop 0
	s_sub_i32 s100, s30, s100
	s_add_i32 s100, s100, 7
	s_lshr_b32 s100, s100, 3
	s_waitcnt lgkmcnt(0)
.LBB0_418:
	global_load_dwordx4 v[18:21], v[12:13], off
	global_load_dwordx4 v[22:25], v[10:11], off
	v_lshl_add_u64 v[10:11], v[10:11], 0, s[70:71]
	v_lshl_add_u64 v[12:13], v[12:13], 0, s[70:71]
	s_cmp_lt_u32 s100, 2
	s_cbranch_scc1 .Lp128_w1
	global_load_dwordx4 v[26:29], v[12:13], off
	global_load_dwordx4 v[30:33], v[10:11], off
	v_lshl_add_u64 v[10:11], v[10:11], 0, s[70:71]
	v_lshl_add_u64 v[12:13], v[12:13], 0, s[70:71]
	s_cmp_lt_u32 s100, 3
	s_cbranch_scc1 .Lp128_w2
	global_load_dwordx4 v[34:37], v[12:13], off
	global_load_dwordx4 v[38:41], v[10:11], off
	v_lshl_add_u64 v[10:11], v[10:11], 0, s[70:71]
	v_lshl_add_u64 v[12:13], v[12:13], 0, s[70:71]
	s_cmp_lt_u32 s100, 4
	s_cbranch_scc1 .Lp128_w3
	global_load_dwordx4 v[44:47], v[12:13], off
	global_load_dwordx4 v[48:51], v[10:11], off
	v_lshl_add_u64 v[10:11], v[10:11], 0, s[70:71]
	v_lshl_add_u64 v[12:13], v[12:13], 0, s[70:71]
	s_waitcnt vmcnt(6)
	v_mfma_f32_16x16x32_bf16 v[0:3], v[18:21], v[22:25], v[0:3]
	s_waitcnt vmcnt(4)
	v_mfma_f32_16x16x32_bf16 v[0:3], v[26:29], v[30:33], v[0:3]
	s_waitcnt vmcnt(2)
	v_mfma_f32_16x16x32_bf16 v[0:3], v[34:37], v[38:41], v[0:3]
	s_waitcnt vmcnt(0)
	v_mfma_f32_16x16x32_bf16 v[0:3], v[44:47], v[48:51], v[0:3]
	s_sub_u32 s100, s100, 4
	s_cmp_lg_u32 s100, 0
	s_cbranch_scc1 .LBB0_418
	s_branch .Lp128_done
.Lp128_w3:
	s_waitcnt vmcnt(4)
	v_mfma_f32_16x16x32_bf16 v[0:3], v[18:21], v[22:25], v[0:3]
	s_waitcnt vmcnt(2)
	v_mfma_f32_16x16x32_bf16 v[0:3], v[26:29], v[30:33], v[0:3]
	s_waitcnt vmcnt(0)
	v_mfma_f32_16x16x32_bf16 v[0:3], v[34:37], v[38:41], v[0:3]
	s_branch .Lp128_done
.Lp128_w2:
	s_waitcnt vmcnt(2)
	v_mfma_f32_16x16x32_bf16 v[0:3], v[18:21], v[22:25], v[0:3]
	s_waitcnt vmcnt(0)
	v_mfma_f32_16x16x32_bf16 v[0:3], v[26:29], v[30:33], v[0:3]
	s_branch .Lp128_done
.Lp128_w1:
	s_waitcnt vmcnt(0)
	v_mfma_f32_16x16x32_bf16 v[0:3], v[18:21], v[22:25], v[0:3]
.Lp128_done:
	s_nop 7
	s_nop 7
	s_or_b64 exec, exec, s[36:37]
